# side workgroups also skip the wait at the ff1->ff2 barrier (their ff2-phase work, next-layer weight transposes, does not depend on ff1)
# baseline (speedup 1.0000x reference)
.LBB0_2135:
	s_or_b64 exec, exec, s[20:21]
	s_waitcnt lgkmcnt(1)
	v_cvt_f32_u32_e32 v4, v2
	s_waitcnt vmcnt(0)
	v_readfirstlane_b32 s0, v3
	buffer_inv sc1
	v_sub_u32_e32 v3, 0, v2
	v_rcp_iflag_f32_e32 v4, v4
	v_add_u32_e32 v5, s0, v1
	v_mul_f32_e32 v4, 0x4f7ffffe, v4
	v_cvt_u32_f32_e32 v4, v4
	v_mul_lo_u32 v1, v3, v4
	v_mul_hi_u32 v1, v4, v1
	v_add_u32_e32 v1, v4, v1
	v_mul_hi_u32 v1, v5, v1
	v_mul_lo_u32 v3, v1, v2
	v_sub_u32_e32 v3, v5, v3
	v_add_u32_e32 v4, 1, v1
	v_cmp_ge_u32_e32 vcc, v3, v2
	s_nop 1
	v_cndmask_b32_e32 v1, v1, v4, vcc
	v_sub_u32_e32 v4, v3, v2
	v_cndmask_b32_e32 v3, v3, v4, vcc
	v_add_u32_e32 v4, 1, v1
	v_cmp_ge_u32_e32 vcc, v3, v2
	v_add_u32_e32 v3, 1, v5
	s_nop 0
	v_cndmask_b32_e32 v1, v1, v4, vcc
	v_mul_lo_u32 v4, v2, v1
	v_add_u32_e32 v2, v4, v2
	v_cmp_ne_u32_e32 vcc, v3, v2
	s_and_saveexec_b64 s[0:1], vcc
	s_xor_b64 s[18:19], exec, s[0:1]
	s_cbranch_execz .LBB0_2149
	v_readlane_b32 s0, v255, 46
	s_cmp_lg_u32 s0, 0
	s_cbranch_scc0 .Lmy_gpoll_b
	s_lshr_b32 s96, s4, 1
	s_add_i32 s96, s96, 0xe51
	s_lshl_b64 s[0:1], s[96:97], 2
	v_readlane_b32 s8, v254, 10
	v_readlane_b32 s9, v254, 11
	s_add_u32 s22, s8, s0
	s_addc_u32 s23, s9, s1
	s_mov_b32 s5, 0
	s_waitcnt lgkmcnt(0)
	s_nop 1
	s_cmpk_lt_i32 s2, 0xc0
	s_cbranch_scc1 .Lmy_lpoll_b
	s_waitcnt vmcnt(0)
	s_branch .LBB0_2149
